# instruction selection: diff-latent loop row-sum scalar add pairs merged into v_pk_add_f32 (11 pairs, same per-component order)
# speedup vs baseline: 1.0039x; 1.0039x over previous
.LBB0_435:
	v_pk_fma_f32 v[96:97], v[96:97], s[58:59], v[210:211] op_sel_hi:[1,0,0] neg_lo:[0,0,1] neg_hi:[0,0,1]
	v_pk_fma_f32 v[98:99], v[98:99], s[58:59], v[210:211] op_sel_hi:[1,0,0] neg_lo:[0,0,1] neg_hi:[0,0,1]
	v_exp_f32_e32 v96, v96
	v_exp_f32_e32 v97, v97
	v_exp_f32_e32 v98, v98
	v_exp_f32_e32 v99, v99
	v_pk_fma_f32 v[100:101], v[100:101], s[58:59], v[210:211] op_sel_hi:[1,0,0] neg_lo:[0,0,1] neg_hi:[0,0,1]
	v_pk_fma_f32 v[102:103], v[102:103], s[58:59], v[210:211] op_sel_hi:[1,0,0] neg_lo:[0,0,1] neg_hi:[0,0,1]
	v_exp_f32_e32 v100, v100
	v_exp_f32_e32 v101, v101
	v_exp_f32_e32 v102, v102
	v_exp_f32_e32 v103, v103
	v_pk_fma_f32 v[104:105], v[104:105], s[58:59], v[210:211] op_sel_hi:[1,0,0] neg_lo:[0,0,1] neg_hi:[0,0,1]
	v_pk_add_f32 v[238:239], v[96:97], 0 op_sel_hi:[1,0]
	v_exp_f32_e32 v104, v104
	v_exp_f32_e32 v105, v105
	v_pk_fma_f32 v[106:107], v[106:107], s[58:59], v[210:211] op_sel_hi:[1,0,0] neg_lo:[0,0,1] neg_hi:[0,0,1]
	v_pk_add_f32 v[238:239], v[98:99], v[238:239]
	v_exp_f32_e32 v106, v106
	v_exp_f32_e32 v107, v107
	v_pk_fma_f32 v[108:109], v[108:109], s[58:59], v[210:211] op_sel_hi:[1,0,0] neg_lo:[0,0,1] neg_hi:[0,0,1]
	v_pk_add_f32 v[238:239], v[100:101], v[238:239]
	v_exp_f32_e32 v108, v108
	v_exp_f32_e32 v109, v109
	v_pk_fma_f32 v[110:111], v[110:111], s[58:59], v[210:211] op_sel_hi:[1,0,0] neg_lo:[0,0,1] neg_hi:[0,0,1]
	v_pk_add_f32 v[238:239], v[102:103], v[238:239]
	v_exp_f32_e32 v110, v110
	v_exp_f32_e32 v111, v111
	v_pk_fma_f32 v[80:81], v[80:81], s[58:59], v[210:211] op_sel_hi:[1,0,0] neg_lo:[0,0,1] neg_hi:[0,0,1]
	v_pk_add_f32 v[238:239], v[104:105], v[238:239]
	v_exp_f32_e32 v240, v80
	v_exp_f32_e32 v241, v81
	v_pk_fma_f32 v[80:81], v[82:83], s[58:59], v[210:211] op_sel_hi:[1,0,0] neg_lo:[0,0,1] neg_hi:[0,0,1]
	v_pk_add_f32 v[238:239], v[106:107], v[238:239]
	v_exp_f32_e32 v242, v80
	v_exp_f32_e32 v243, v81
	v_pk_fma_f32 v[80:81], v[84:85], s[58:59], v[210:211] op_sel_hi:[1,0,0] neg_lo:[0,0,1] neg_hi:[0,0,1]
	v_pk_add_f32 v[238:239], v[108:109], v[238:239]
	v_exp_f32_e32 v84, v80
	v_exp_f32_e32 v85, v81
	v_pk_add_f32 v[80:81], v[110:111], v[238:239]
	v_cvt_pk_bf16_f32 v82, v100, v101
	v_pk_add_f32 v[80:81], v[240:241], v[80:81]
	v_cvt_pk_bf16_f32 v83, v102, v103
	v_pk_add_f32 v[80:81], v[242:243], v[80:81]
	s_add_i32 s56, s56, 64
	v_pk_add_f32 v[238:239], v[84:85], v[80:81]
	v_pk_fma_f32 v[80:81], v[86:87], s[58:59], v[210:211] op_sel_hi:[1,0,0] neg_lo:[0,0,1] neg_hi:[0,0,1]
	s_add_u32 s0, s0, 0x80
	v_exp_f32_e32 v86, v80
	v_exp_f32_e32 v87, v81
	v_cvt_pk_bf16_f32 v80, v96, v97
	v_cvt_pk_bf16_f32 v81, v98, v99
	s_addc_u32 s1, s1, 0
	v_pk_add_f32 v[96:97], v[86:87], v[238:239]
	v_mfma_f32_32x32x16_bf16 v[64:79], v[6:9], v[80:83], v[64:79]
	v_fma_f32 v6, v88, s58, -v210
	v_fma_f32 v7, v89, s58, -v210
	v_cvt_pk_bf16_f32 v8, v108, v109
	v_exp_f32_e32 v88, v6
	v_exp_f32_e32 v89, v7
	v_pk_fma_f32 v[6:7], v[90:91], s[58:59], v[210:211] op_sel_hi:[1,0,0] neg_lo:[0,0,1] neg_hi:[0,0,1]
	v_cvt_pk_bf16_f32 v9, v110, v111
	v_exp_f32_e32 v90, v6
	v_mfma_f32_32x32x16_bf16 v[32:47], v[10:13], v[80:83], v[32:47]
	v_exp_f32_e32 v91, v7
	v_pk_fma_f32 v[6:7], v[92:93], s[58:59], v[210:211] op_sel_hi:[1,0,0] neg_lo:[0,0,1] neg_hi:[0,0,1]
	s_add_u32 s2, s2, 0x2000
	v_exp_f32_e32 v10, v6
	v_exp_f32_e32 v11, v7
	v_cvt_pk_bf16_f32 v6, v104, v105
	v_cvt_pk_bf16_f32 v7, v106, v107
	s_addc_u32 s3, s3, 0
	s_cmpk_lg_i32 s17, 0x44
	v_mfma_f32_32x32x16_bf16 v[64:79], v[2:5], v[6:9], v[64:79]
	v_cvt_pk_bf16_f32 v4, v240, v241
	v_cvt_pk_bf16_f32 v5, v242, v243
	v_fma_f32 v2, v94, s58, -v210
	v_fma_f32 v3, v95, s58, -v210
	v_exp_f32_e32 v12, v2
	v_exp_f32_e32 v13, v3
	v_pk_add_f32 v[2:3], v[88:89], v[96:97]
	v_mfma_f32_32x32x16_bf16 v[32:47], v[144:147], v[6:9], v[32:47]
	v_pk_add_f32 v[8:9], v[180:181], 0 op_sel_hi:[1,0]
	v_cvt_pk_bf16_f32 v6, v84, v85
	v_cvt_pk_bf16_f32 v7, v86, v87
	v_pk_add_f32 v[8:9], v[178:179], v[8:9]
	v_pk_add_f32 v[2:3], v[90:91], v[2:3]
	v_pk_add_f32 v[8:9], v[182:183], v[8:9]
	v_pk_add_f32 v[2:3], v[10:11], v[2:3]
	v_mfma_f32_32x32x16_bf16 v[64:79], v[148:151], v[4:7], v[64:79]
	v_pk_add_f32 v[8:9], v[184:185], v[8:9]
	v_pk_add_f32 v[2:3], v[12:13], v[2:3]
	v_pk_add_f32 v[8:9], v[186:187], v[8:9]
	v_add_f32_e32 v3, v2, v3
	v_pk_add_f32 v[8:9], v[188:189], v[8:9]
	v_fmac_f32_e32 v3, v236, v212
	v_pk_add_f32 v[8:9], v[194:195], v[8:9]
	v_mfma_f32_32x32x16_bf16 v[32:47], v[152:155], v[4:7], v[32:47]
	v_pk_add_f32 v[8:9], v[200:201], v[8:9]
	v_cvt_pk_bf16_f32 v6, v88, v89
	v_pk_add_f32 v[4:5], v[198:199], v[8:9]
	v_cvt_pk_bf16_f32 v7, v90, v91
	v_pk_add_f32 v[4:5], v[204:205], v[4:5]
	v_cvt_pk_bf16_f32 v8, v10, v11
	v_cvt_pk_bf16_f32 v9, v12, v13
	v_pk_add_f32 v[4:5], v[208:209], v[4:5]
	s_barrier
	v_mfma_f32_32x32x16_bf16 v[64:79], v[156:159], v[6:9], v[64:79]
	v_pk_add_f32 v[4:5], v[190:191], v[4:5]
	v_pk_add_f32 v[4:5], v[192:193], v[4:5]
	v_pk_add_f32 v[4:5], v[196:197], v[4:5]
	v_pk_add_f32 v[4:5], v[202:203], v[4:5]
	v_mfma_f32_32x32x16_bf16 v[32:47], v[160:163], v[6:9], v[32:47]
	v_pk_add_f32 v[4:5], v[206:207], v[4:5]
	v_add_f32_e32 v4, v4, v5
	v_fmac_f32_e32 v4, v15, v14
	s_cbranch_scc1 .LBB0_425
	ds_bpermute_b32 v0, v167, v4
	s_movk_i32 s0, 0x90
	v_mul_lo_u32 v15, v234, s0
	v_readlane_b32 s2, v255, 9
	v_readlane_b32 s3, v255, 10
	s_waitcnt lgkmcnt(0)
	v_add_f32_e32 v0, v4, v0
	v_div_scale_f32 v2, s[0:1], v0, v0, 1.0
	v_rcp_f32_e32 v4, v2
	s_mov_b64 s[6:7], -1
	v_fma_f32 v5, -v2, v4, 1.0
	v_fmac_f32_e32 v4, v5, v4
	v_div_scale_f32 v5, vcc, 1.0, v0, 1.0
	v_mul_f32_e32 v6, v5, v4
	v_fma_f32 v7, -v2, v6, v5
	v_fmac_f32_e32 v6, v7, v4
	v_fma_f32 v2, -v2, v6, v5
	v_div_fmas_f32 v2, v2, v4, v6
	v_div_fixup_f32 v0, v2, v0, 1.0
	ds_bpermute_b32 v2, v167, v3
	s_waitcnt lgkmcnt(0)
	v_add_f32_e32 v2, v3, v2
	v_div_scale_f32 v3, s[0:1], v2, v2, 1.0
	v_rcp_f32_e32 v4, v3
	v_readlane_b32 s0, v255, 7
	v_readlane_b32 s1, v255, 8
	v_fma_f32 v5, -v3, v4, 1.0
	v_fmac_f32_e32 v4, v5, v4
	v_div_scale_f32 v5, vcc, 1.0, v2, 1.0
	v_mul_f32_e32 v6, v5, v4
	v_fma_f32 v7, -v3, v6, v5
	v_fmac_f32_e32 v6, v7, v4
	v_fma_f32 v3, -v3, v6, v5
	v_div_fmas_f32 v3, v3, v4, v6
	v_div_fixup_f32 v14, v3, v2, 1.0
	global_load_dwordx4 v[2:5], v1, s[0:1] offset:48
	global_load_dwordx4 v[6:9], v1, s[0:1] offset:32
	global_load_dwordx4 v[10:13], v1, s[0:1] offset:16
	global_load_dwordx4 v[80:83], v1, s[0:1]
	global_load_dwordx4 v[84:87], v1, s[0:1] offset:176
	global_load_dwordx4 v[88:91], v1, s[0:1] offset:160
	global_load_dwordx4 v[92:95], v1, s[0:1] offset:144
	global_load_dwordx4 v[96:99], v1, s[0:1] offset:128
	global_load_dwordx4 v[100:103], v1, s[0:1] offset:304
	global_load_dwordx4 v[104:107], v1, s[0:1] offset:288
	global_load_dwordx4 v[108:111], v1, s[0:1] offset:272
	global_load_dwordx4 v[112:115], v1, s[0:1] offset:256
	global_load_dwordx4 v[116:119], v1, s[0:1] offset:432
	global_load_dwordx4 v[120:123], v1, s[0:1] offset:416
	global_load_dwordx4 v[124:127], v1, s[0:1] offset:400
	global_load_dwordx4 v[128:131], v1, s[0:1] offset:384
	s_waitcnt vmcnt(8)
	v_fma_f32 v132, v80, v96, 0
	v_fmac_f32_e32 v132, v81, v97
	s_waitcnt vmcnt(0)
	v_fma_f32 v133, v112, v128, 0
	v_fmac_f32_e32 v132, v82, v98
	v_fmac_f32_e32 v133, v113, v129
	v_fmac_f32_e32 v132, v83, v99
	v_fmac_f32_e32 v133, v114, v130
	v_fmac_f32_e32 v132, v10, v92
	v_fmac_f32_e32 v133, v115, v131
	v_fmac_f32_e32 v132, v11, v93
	v_fmac_f32_e32 v133, v108, v124
	v_fmac_f32_e32 v132, v12, v94
	v_fmac_f32_e32 v133, v109, v125
	v_fmac_f32_e32 v132, v13, v95
	v_fmac_f32_e32 v133, v110, v126
	v_fmac_f32_e32 v132, v6, v88
	v_fmac_f32_e32 v133, v111, v127
	v_fmac_f32_e32 v132, v7, v89
	v_fmac_f32_e32 v133, v104, v120
	v_fmac_f32_e32 v132, v8, v90
	v_fmac_f32_e32 v133, v105, v121
	v_fmac_f32_e32 v132, v9, v91
	v_fmac_f32_e32 v133, v106, v122
	v_fmac_f32_e32 v132, v2, v84
	v_fmac_f32_e32 v133, v107, v123
	v_fmac_f32_e32 v132, v3, v85
	v_fmac_f32_e32 v133, v100, v116
	v_fmac_f32_e32 v132, v4, v86
	v_fmac_f32_e32 v133, v101, v117
	v_fmac_f32_e32 v132, v5, v87
	global_load_dwordx4 v[2:5], v1, s[0:1] offset:80
	global_load_dwordx4 v[92:95], v1, s[0:1] offset:64
	global_load_dwordx4 v[6:9], v1, s[0:1] offset:112
	global_load_dwordx4 v[10:13], v1, s[0:1] offset:96
	global_load_dwordx4 v[84:87], v1, s[0:1] offset:208
	global_load_dwordx4 v[104:107], v1, s[0:1] offset:192
	global_load_dwordx4 v[80:83], v1, s[0:1] offset:240
	global_load_dwordx4 v[88:91], v1, s[0:1] offset:224
	v_fmac_f32_e32 v133, v102, v118
	v_fmac_f32_e32 v133, v103, v119
	global_load_dwordx4 v[96:99], v1, s[0:1] offset:336
	global_load_dwordx4 v[120:123], v1, s[0:1] offset:320
	global_load_dwordx4 v[100:103], v1, s[0:1] offset:368
	global_load_dwordx4 v[108:111], v1, s[0:1] offset:352
	global_load_dwordx4 v[116:119], v1, s[0:1] offset:464
	global_load_dwordx4 v[124:127], v1, s[0:1] offset:448
	global_load_dwordx4 v[112:115], v1, s[0:1] offset:496
	global_load_dwordx4 v[128:131], v1, s[0:1] offset:480
	s_mov_b32 s0, 0x7060302
	s_waitcnt vmcnt(10)
	v_fmac_f32_e32 v132, v92, v104
	v_fmac_f32_e32 v132, v93, v105
	v_fmac_f32_e32 v132, v94, v106
	s_waitcnt vmcnt(2)
	v_fmac_f32_e32 v133, v120, v124
	v_fmac_f32_e32 v133, v121, v125
	v_fmac_f32_e32 v132, v95, v107
	v_fmac_f32_e32 v133, v122, v126
	v_fmac_f32_e32 v132, v2, v84
	v_fmac_f32_e32 v133, v123, v127
	v_fmac_f32_e32 v132, v3, v85
	v_fmac_f32_e32 v133, v96, v116
	v_fmac_f32_e32 v132, v4, v86
	v_fmac_f32_e32 v133, v97, v117
	v_fmac_f32_e32 v132, v5, v87
	v_pk_mul_f32 v[2:3], v[10:11], v[88:89]
	v_fmac_f32_e32 v133, v98, v118
	v_add_f32_e32 v2, v132, v2
	v_fmac_f32_e32 v133, v99, v119
	v_add_f32_e32 v4, v2, v3
	s_waitcnt vmcnt(0)
	v_pk_mul_f32 v[2:3], v[108:109], v[128:129]
	s_nop 0
	v_add_f32_e32 v2, v133, v2
	v_add_f32_e32 v5, v2, v3
	v_pk_mul_f32 v[2:3], v[12:13], v[90:91]
	s_nop 0
	v_add_f32_e32 v2, v4, v2
	v_add_f32_e32 v4, v2, v3
	v_pk_mul_f32 v[2:3], v[110:111], v[130:131]
	s_nop 0
	v_add_f32_e32 v2, v5, v2
	v_add_f32_e32 v5, v2, v3
	v_pk_mul_f32 v[2:3], v[6:7], v[80:81]
	v_add3_u32 v81, v15, v171, v235
	v_add_f32_e32 v2, v4, v2
	v_add_f32_e32 v4, v2, v3
	v_pk_mul_f32 v[2:3], v[100:101], v[112:113]
	s_nop 0
	v_add_f32_e32 v2, v5, v2
	v_add_f32_e32 v5, v2, v3
	v_pk_mul_f32 v[2:3], v[8:9], v[82:83]
	s_nop 0
	v_add_f32_e32 v2, v4, v2
	v_add_f32_e32 v4, v2, v3
	v_pk_mul_f32 v[2:3], v[102:103], v[114:115]
	s_nop 0
	v_add_f32_e32 v2, v5, v2
	v_add_f32_e32 v2, v2, v3
	v_mul_f32_e32 v3, 0x3fb8aa3b, v4
	v_mul_f32_e32 v2, 0x3fb8aa3b, v2
	v_exp_f32_e32 v3, v3
	v_exp_f32_e32 v2, v2
	s_nop 0
	v_sub_f32_e32 v2, v3, v2
	v_add_f32_e32 v80, v232, v2
	v_pk_mul_f32 v[4:5], v[64:65], v[80:81] op_sel_hi:[1,0]
	v_pk_mul_f32 v[2:3], v[66:67], v[80:81] op_sel_hi:[1,0]
	v_pk_mul_f32 v[4:5], v[14:15], v[4:5] op_sel_hi:[0,1]
	v_pk_fma_f32 v[66:67], v[48:49], v[0:1], v[4:5] op_sel_hi:[1,0,1] neg_lo:[0,0,1] neg_hi:[0,0,1]
	v_pk_mul_f32 v[2:3], v[14:15], v[2:3] op_sel_hi:[0,1]
	v_mul_f32_e32 v82, v67, v67
	v_pk_fma_f32 v[64:65], v[50:51], v[0:1], v[2:3] op_sel_hi:[1,0,1] neg_lo:[0,0,1] neg_hi:[0,0,1]
	v_fmac_f32_e32 v82, v66, v66
	global_load_dwordx4 v[2:5], v166, s[2:3]
	v_pk_mul_f32 v[8:9], v[68:69], v[80:81] op_sel_hi:[1,0]
	v_fmac_f32_e32 v82, v64, v64
	v_pk_mul_f32 v[8:9], v[14:15], v[8:9] op_sel_hi:[0,1]
	v_fmac_f32_e32 v82, v65, v65
	v_pk_mul_f32 v[6:7], v[70:71], v[80:81] op_sel_hi:[1,0]
	v_pk_fma_f32 v[52:53], v[52:53], v[0:1], v[8:9] op_sel_hi:[1,0,1] neg_lo:[0,0,1] neg_hi:[0,0,1]
	v_pk_mul_f32 v[6:7], v[14:15], v[6:7] op_sel_hi:[0,1]
	v_fmac_f32_e32 v82, v52, v52
	v_pk_fma_f32 v[54:55], v[54:55], v[0:1], v[6:7] op_sel_hi:[1,0,1] neg_lo:[0,0,1] neg_hi:[0,0,1]
	v_fmac_f32_e32 v82, v53, v53
	global_load_dwordx4 v[6:9], v166, s[2:3] offset:32
	v_pk_mul_f32 v[12:13], v[72:73], v[80:81] op_sel_hi:[1,0]
	v_fmac_f32_e32 v82, v54, v54
	v_pk_mul_f32 v[12:13], v[14:15], v[12:13] op_sel_hi:[0,1]
	v_fmac_f32_e32 v82, v55, v55
	v_pk_mul_f32 v[10:11], v[74:75], v[80:81] op_sel_hi:[1,0]
	v_pk_fma_f32 v[56:57], v[56:57], v[0:1], v[12:13] op_sel_hi:[1,0,1] neg_lo:[0,0,1] neg_hi:[0,0,1]
	v_pk_mul_f32 v[10:11], v[14:15], v[10:11] op_sel_hi:[0,1]
	v_fmac_f32_e32 v82, v56, v56
	v_pk_fma_f32 v[58:59], v[58:59], v[0:1], v[10:11] op_sel_hi:[1,0,1] neg_lo:[0,0,1] neg_hi:[0,0,1]
	v_fmac_f32_e32 v82, v57, v57
	v_pk_mul_f32 v[50:51], v[76:77], v[80:81] op_sel_hi:[1,0]
	v_fmac_f32_e32 v82, v58, v58
	global_load_dwordx4 v[10:13], v166, s[2:3] offset:64
	v_pk_mul_f32 v[50:51], v[14:15], v[50:51] op_sel_hi:[0,1]
	v_fmac_f32_e32 v82, v59, v59
	v_pk_mul_f32 v[48:49], v[78:79], v[80:81] op_sel_hi:[1,0]
	v_pk_fma_f32 v[60:61], v[60:61], v[0:1], v[50:51] op_sel_hi:[1,0,1] neg_lo:[0,0,1] neg_hi:[0,0,1]
	v_pk_mul_f32 v[48:49], v[14:15], v[48:49] op_sel_hi:[0,1]
	v_fmac_f32_e32 v82, v60, v60
	v_pk_fma_f32 v[62:63], v[62:63], v[0:1], v[48:49] op_sel_hi:[1,0,1] neg_lo:[0,0,1] neg_hi:[0,0,1]
	v_fmac_f32_e32 v82, v61, v61
	v_pk_mul_f32 v[32:33], v[32:33], v[80:81] op_sel_hi:[1,0]
	v_fmac_f32_e32 v82, v62, v62
	global_load_dwordx4 v[48:51], v166, s[2:3] offset:96
	v_pk_mul_f32 v[32:33], v[14:15], v[32:33] op_sel_hi:[0,1]
	v_fmac_f32_e32 v82, v63, v63
	v_pk_mul_f32 v[34:35], v[34:35], v[80:81] op_sel_hi:[1,0]
	v_pk_fma_f32 v[32:33], v[16:17], v[0:1], v[32:33] op_sel_hi:[1,0,1] neg_lo:[0,0,1] neg_hi:[0,0,1]
	v_pk_mul_f32 v[34:35], v[14:15], v[34:35] op_sel_hi:[0,1]
	v_fmac_f32_e32 v82, v32, v32
	v_pk_fma_f32 v[34:35], v[18:19], v[0:1], v[34:35] op_sel_hi:[1,0,1] neg_lo:[0,0,1] neg_hi:[0,0,1]
	v_fmac_f32_e32 v82, v33, v33
	v_pk_mul_f32 v[36:37], v[36:37], v[80:81] op_sel_hi:[1,0]
	v_fmac_f32_e32 v82, v34, v34
	v_pk_mul_f32 v[38:39], v[38:39], v[80:81] op_sel_hi:[1,0]
	v_pk_mul_f32 v[36:37], v[14:15], v[36:37] op_sel_hi:[0,1]
	v_fmac_f32_e32 v82, v35, v35
	global_load_dwordx4 v[16:19], v166, s[2:3] offset:128
	v_pk_mul_f32 v[38:39], v[14:15], v[38:39] op_sel_hi:[0,1]
	v_pk_fma_f32 v[36:37], v[20:21], v[0:1], v[36:37] op_sel_hi:[1,0,1] neg_lo:[0,0,1] neg_hi:[0,0,1]
	v_pk_fma_f32 v[38:39], v[22:23], v[0:1], v[38:39] op_sel_hi:[1,0,1] neg_lo:[0,0,1] neg_hi:[0,0,1]
	v_fmac_f32_e32 v82, v36, v36
	v_pk_mul_f32 v[20:21], v[38:39], v[38:39]
	v_fmac_f32_e32 v82, v37, v37
	v_pk_mul_f32 v[40:41], v[40:41], v[80:81] op_sel_hi:[1,0]
	v_add_f32_e32 v20, v20, v82
	v_pk_mul_f32 v[42:43], v[42:43], v[80:81] op_sel_hi:[1,0]
	v_pk_mul_f32 v[40:41], v[14:15], v[40:41] op_sel_hi:[0,1]
	v_add_f32_e32 v68, v21, v20
	global_load_dwordx4 v[20:23], v166, s[2:3] offset:160
	v_pk_mul_f32 v[42:43], v[14:15], v[42:43] op_sel_hi:[0,1]
	v_pk_fma_f32 v[40:41], v[24:25], v[0:1], v[40:41] op_sel_hi:[1,0,1] neg_lo:[0,0,1] neg_hi:[0,0,1]
	v_pk_fma_f32 v[42:43], v[26:27], v[0:1], v[42:43] op_sel_hi:[1,0,1] neg_lo:[0,0,1] neg_hi:[0,0,1]
	v_pk_mul_f32 v[26:27], v[40:41], v[40:41]
	v_pk_mul_f32 v[24:25], v[42:43], v[42:43]
	v_add_f32_e32 v26, v26, v68
	v_add_f32_e32 v26, v27, v26
	v_add_f32_e32 v24, v24, v26
	v_add_f32_e32 v68, v25, v24
	global_load_dwordx4 v[24:27], v166, s[2:3] offset:192
	v_pk_mul_f32 v[44:45], v[44:45], v[80:81] op_sel_hi:[1,0]
	v_pk_mul_f32 v[46:47], v[46:47], v[80:81] op_sel_hi:[1,0]
	v_pk_mul_f32 v[44:45], v[14:15], v[44:45] op_sel_hi:[0,1]
	v_pk_mul_f32 v[46:47], v[14:15], v[46:47] op_sel_hi:[0,1]
	v_pk_fma_f32 v[28:29], v[28:29], v[0:1], v[44:45] op_sel_hi:[1,0,1] neg_lo:[0,0,1] neg_hi:[0,0,1]
	v_pk_fma_f32 v[30:31], v[30:31], v[0:1], v[46:47] op_sel_hi:[1,0,1] neg_lo:[0,0,1] neg_hi:[0,0,1]
	v_pk_mul_f32 v[46:47], v[28:29], v[28:29]
	v_pk_mul_f32 v[44:45], v[30:31], v[30:31]
	v_add_f32_e32 v0, v46, v68
	v_add_f32_e32 v0, v47, v0
	v_add_f32_e32 v0, v44, v0
	v_add_f32_e32 v0, v45, v0
	ds_bpermute_b32 v14, v167, v0
	s_waitcnt lgkmcnt(0)
	v_add_f32_e32 v0, v0, v14
	v_fmamk_f32 v0, v0, 0x3c800000, v213
	v_cmp_gt_f32_e32 vcc, s54, v0
	v_mul_f32_e32 v14, 0x4b800000, v0
	s_nop 0
	v_cndmask_b32_e32 v0, v0, v14, vcc
	v_rsq_f32_e32 v0, v0
	s_nop 0
	v_mul_f32_e32 v14, 0x45800000, v0
	v_cndmask_b32_e32 v0, v0, v14, vcc
	v_mul_f32_e32 v14, v233, v0
	v_pk_mul_f32 v[46:47], v[66:67], v[14:15] op_sel_hi:[1,0]
	v_pk_mul_f32 v[44:45], v[64:65], v[14:15] op_sel_hi:[1,0]
	s_waitcnt vmcnt(6)
	v_pk_mul_f32 v[2:3], v[2:3], v[46:47]
	v_pk_mul_f32 v[4:5], v[4:5], v[44:45]
	v_bfe_u32 v45, v3, 16, 1
	v_bfe_u32 v46, v2, 16, 1
	v_bfe_u32 v0, v5, 16, 1
	v_bfe_u32 v44, v4, 16, 1
	v_add3_u32 v2, v2, v46, s37
	v_add3_u32 v45, v3, v45, s37
	v_add3_u32 v3, v4, v44, s37
	v_add3_u32 v0, v5, v0, s37
	v_perm_b32 v2, v45, v2, s0
	v_pk_mul_f32 v[4:5], v[54:55], v[14:15] op_sel_hi:[1,0]
	v_pk_mul_f32 v[44:45], v[52:53], v[14:15] op_sel_hi:[1,0]
	s_waitcnt vmcnt(5)
	v_pk_mul_f32 v[4:5], v[8:9], v[4:5]
	v_pk_mul_f32 v[6:7], v[6:7], v[44:45]
	v_perm_b32 v3, v0, v3, s0
	v_bfe_u32 v0, v5, 16, 1
	v_bfe_u32 v8, v4, 16, 1
	v_bfe_u32 v9, v7, 16, 1
	v_bfe_u32 v44, v6, 16, 1
	v_add3_u32 v6, v6, v44, s37
	v_add3_u32 v7, v7, v9, s37
	v_add3_u32 v4, v4, v8, s37
	v_add3_u32 v0, v5, v0, s37
	v_perm_b32 v5, v0, v4, s0
	v_perm_b32 v4, v7, v6, s0
	v_add_u32_e32 v0, 0x9800, v81
	ds_write2_b64 v0, v[2:3], v[4:5] offset1:2
	v_pk_mul_f32 v[2:3], v[58:59], v[14:15] op_sel_hi:[1,0]
	v_pk_mul_f32 v[4:5], v[56:57], v[14:15] op_sel_hi:[1,0]
	s_waitcnt vmcnt(4)
	v_pk_mul_f32 v[2:3], v[12:13], v[2:3]
	v_pk_mul_f32 v[4:5], v[10:11], v[4:5]
	v_bfe_u32 v6, v3, 16, 1
	v_bfe_u32 v7, v2, 16, 1
	v_bfe_u32 v8, v5, 16, 1
	v_bfe_u32 v9, v4, 16, 1
	v_add3_u32 v4, v4, v9, s37
	v_add3_u32 v5, v5, v8, s37
	v_add3_u32 v2, v2, v7, s37
	v_add3_u32 v3, v3, v6, s37
	v_perm_b32 v3, v3, v2, s0
	v_perm_b32 v2, v5, v4, s0
	v_pk_mul_f32 v[4:5], v[62:63], v[14:15] op_sel_hi:[1,0]
	v_pk_mul_f32 v[6:7], v[60:61], v[14:15] op_sel_hi:[1,0]
	s_waitcnt vmcnt(3)
	v_pk_mul_f32 v[4:5], v[50:51], v[4:5]
	v_pk_mul_f32 v[6:7], v[48:49], v[6:7]
	v_bfe_u32 v8, v5, 16, 1
	v_bfe_u32 v9, v4, 16, 1
	v_bfe_u32 v10, v7, 16, 1
	v_bfe_u32 v11, v6, 16, 1
	v_add3_u32 v6, v6, v11, s37
	v_add3_u32 v7, v7, v10, s37
	v_add3_u32 v4, v4, v9, s37
	v_add3_u32 v5, v5, v8, s37
	v_perm_b32 v5, v5, v4, s0
	v_perm_b32 v4, v7, v6, s0
	ds_write2_b64 v0, v[2:3], v[4:5] offset0:4 offset1:6
	v_pk_mul_f32 v[2:3], v[34:35], v[14:15] op_sel_hi:[1,0]
	v_pk_mul_f32 v[4:5], v[32:33], v[14:15] op_sel_hi:[1,0]
	s_waitcnt vmcnt(2)
	v_pk_mul_f32 v[2:3], v[18:19], v[2:3]
	v_pk_mul_f32 v[4:5], v[16:17], v[4:5]
	v_bfe_u32 v6, v3, 16, 1
	v_bfe_u32 v7, v2, 16, 1
	v_bfe_u32 v8, v5, 16, 1
	v_bfe_u32 v9, v4, 16, 1
	v_add3_u32 v4, v4, v9, s37
	v_add3_u32 v5, v5, v8, s37
	v_add3_u32 v2, v2, v7, s37
	v_add3_u32 v3, v3, v6, s37
	v_perm_b32 v3, v3, v2, s0
	v_perm_b32 v2, v5, v4, s0
	v_pk_mul_f32 v[4:5], v[38:39], v[14:15] op_sel_hi:[1,0]
	v_pk_mul_f32 v[6:7], v[36:37], v[14:15] op_sel_hi:[1,0]
	s_waitcnt vmcnt(1)
	v_pk_mul_f32 v[4:5], v[22:23], v[4:5]
	v_pk_mul_f32 v[6:7], v[20:21], v[6:7]
	v_bfe_u32 v8, v5, 16, 1
	v_bfe_u32 v9, v4, 16, 1
	v_bfe_u32 v10, v7, 16, 1
	v_bfe_u32 v11, v6, 16, 1
	v_add3_u32 v6, v6, v11, s37
	v_add3_u32 v7, v7, v10, s37
	v_add3_u32 v4, v4, v9, s37
	v_add3_u32 v5, v5, v8, s37
	v_perm_b32 v5, v5, v4, s0
	v_perm_b32 v4, v7, v6, s0
	ds_write2_b64 v0, v[2:3], v[4:5] offset0:8 offset1:10
	v_pk_mul_f32 v[2:3], v[42:43], v[14:15] op_sel_hi:[1,0]
	v_pk_mul_f32 v[4:5], v[40:41], v[14:15] op_sel_hi:[1,0]
	s_waitcnt vmcnt(0)
	v_pk_mul_f32 v[2:3], v[26:27], v[2:3]
	v_pk_mul_f32 v[4:5], v[24:25], v[4:5]
	v_bfe_u32 v6, v3, 16, 1
	v_bfe_u32 v7, v2, 16, 1
	v_bfe_u32 v8, v5, 16, 1
	v_bfe_u32 v9, v4, 16, 1
	v_add3_u32 v4, v4, v9, s37
	v_add3_u32 v5, v5, v8, s37
	v_add3_u32 v2, v2, v7, s37
	v_add3_u32 v3, v3, v6, s37
	v_perm_b32 v7, v3, v2, s0
	v_perm_b32 v6, v5, v4, s0
	global_load_dwordx4 v[2:5], v166, s[2:3] offset:224
	v_pk_mul_f32 v[8:9], v[28:29], v[14:15] op_sel_hi:[1,0]
	v_pk_mul_f32 v[10:11], v[30:31], v[14:15] op_sel_hi:[1,0]
	s_waitcnt vmcnt(0)
	v_pk_mul_f32 v[2:3], v[8:9], v[2:3]
	v_pk_mul_f32 v[4:5], v[10:11], v[4:5]
	v_bfe_u32 v8, v3, 16, 1
	v_bfe_u32 v9, v2, 16, 1
	v_bfe_u32 v10, v5, 16, 1
	v_bfe_u32 v11, v4, 16, 1
	v_add3_u32 v4, v4, v11, s37
	v_add3_u32 v5, v5, v10, s37
	v_add3_u32 v2, v2, v9, s37
	v_add3_u32 v3, v3, v8, s37
	v_perm_b32 v2, v3, v2, s0
	v_perm_b32 v3, v5, v4, s0
	s_lshl_b32 s0, s12, 12
	s_or_b32 s0, s0, s11
	s_addk_i32 s0, 0x2000
	ds_write2_b64 v0, v[6:7], v[2:3] offset0:12 offset1:14
	v_add_u32_e32 v6, s0, v234
	v_lshrrev_b32_e32 v7, 3, v165
	v_lshlrev_b32_e32 v0, 1, v164
	s_lshl_b32 s0, s10, 7
	v_mul_u32_u24_e32 v2, 0x90, v7
	v_or_b32_e32 v6, v6, v7
	s_add_u32 s0, s94, s0
	v_add3_u32 v10, v15, v0, v2
	v_ashrrev_i32_e32 v7, 31, v6
	s_waitcnt lgkmcnt(0)
	s_barrier
	s_addc_u32 s1, s95, 0
	ds_read_b128 v[2:5], v10 offset:38912
	v_lshlrev_b64 v[8:9], 11, v[6:7]
	v_lshl_add_u64 v[8:9], s[0:1], 0, v[8:9]
	v_lshl_add_u64 v[8:9], v[8:9], 0, v[0:1]
	v_add_co_u32_e32 v8, vcc, s35, v8
	s_nop 1
	v_addc_co_u32_e32 v9, vcc, 0, v9, vcc
	s_waitcnt lgkmcnt(0)
	global_store_dwordx4 v[8:9], v[2:5], off offset:1280
	v_or_b32_e32 v8, 8, v6
	v_ashrrev_i32_e32 v9, 31, v8
	ds_read_b128 v[2:5], v10 offset:40064
	v_lshlrev_b64 v[8:9], 11, v[8:9]
	v_lshl_add_u64 v[8:9], s[0:1], 0, v[8:9]
	v_lshl_add_u64 v[8:9], v[8:9], 0, v[0:1]
	v_add_co_u32_e32 v8, vcc, s35, v8
	s_nop 1
	v_addc_co_u32_e32 v9, vcc, 0, v9, vcc
	s_waitcnt lgkmcnt(0)
	global_store_dwordx4 v[8:9], v[2:5], off offset:1280
	v_or_b32_e32 v8, 16, v6
	v_ashrrev_i32_e32 v9, 31, v8
	ds_read_b128 v[2:5], v10 offset:41216
	v_lshlrev_b64 v[8:9], 11, v[8:9]
	v_lshl_add_u64 v[8:9], s[0:1], 0, v[8:9]
	v_lshl_add_u64 v[8:9], v[8:9], 0, v[0:1]
	v_add_co_u32_e32 v8, vcc, s35, v8
	v_or_b32_e32 v6, 24, v6
	s_nop 0
	v_addc_co_u32_e32 v9, vcc, 0, v9, vcc
	v_ashrrev_i32_e32 v7, 31, v6
	s_waitcnt lgkmcnt(0)
	global_store_dwordx4 v[8:9], v[2:5], off offset:1280
	ds_read_b128 v[2:5], v10 offset:42368
	v_lshlrev_b64 v[6:7], 11, v[6:7]
	v_lshl_add_u64 v[6:7], s[0:1], 0, v[6:7]
	v_lshl_add_u64 v[6:7], v[6:7], 0, v[0:1]
	v_add_co_u32_e32 v6, vcc, 0x10885000, v6
	s_nop 1
	v_addc_co_u32_e32 v7, vcc, 0, v7, vcc
	s_waitcnt lgkmcnt(0)
	global_store_dwordx4 v[6:7], v[2:5], off offset:1280
	s_barrier
